# phase0 keeps only layer-0 W_in transposes; other weight transposes run inside layer-0 mixer pass-1 job loop, de-phased per block group (hand-written packed LDS transpose)
# speedup vs baseline: 1.0097x; 1.0097x over previous
.LBB0_61:
	v_mov_b32_e32 v32, v180
	s_cmpk_gt_i32 s86, 0xa07
	s_cbranch_scc1 .LBB0_106
	v_readlane_b32 s0, v254, 44
	v_readlane_b32 s52, v254, 60
	v_readlane_b32 s4, v254, 48
	v_readlane_b32 s5, v254, 49
	v_readlane_b32 s8, v254, 52
	v_readlane_b32 s9, v254, 53
	v_readlane_b32 s12, v254, 56
	v_readlane_b32 s13, v254, 57
	v_readlane_b32 s53, v254, 61
	v_readlane_b32 s54, v254, 62
	v_readlane_b32 s55, v254, 63
	v_readlane_b32 s56, v253, 0
	v_readlane_b32 s57, v253, 1
	v_readlane_b32 s58, v253, 2
	v_readlane_b32 s59, v253, 3
	v_readlane_b32 s60, v253, 4
	v_readlane_b32 s61, v253, 5
	v_readlane_b32 s62, v253, 6
	v_readlane_b32 s63, v253, 7
	v_readlane_b32 s64, v253, 8
	v_readlane_b32 s65, v253, 9
	v_readlane_b32 s66, v253, 10
	v_readlane_b32 s67, v253, 11
	s_mov_b64 s[4:5], s[58:59]
	s_mov_b64 s[8:9], s[64:65]
	s_mov_b64 s[12:13], s[66:67]
	v_readlane_b32 s52, v254, 12
	v_readlane_b32 s1, v254, 45
	v_readlane_b32 s2, v254, 46
	v_readlane_b32 s3, v254, 47
	v_readlane_b32 s10, v254, 54
	v_readlane_b32 s11, v254, 55
	v_readlane_b32 s53, v254, 13
	s_mov_b64 s[2:3], s[10:11]
	s_mov_b64 s[0:1], s[52:53]
	s_cmpk_gt_i32 s86, 0x140f
	v_readlane_b32 s6, v254, 50
	v_readlane_b32 s7, v254, 51
	v_readlane_b32 s14, v254, 58
	v_readlane_b32 s15, v254, 59
	v_readlane_b32 s54, v254, 14
	v_readlane_b32 s55, v254, 15
	v_readlane_b32 s56, v254, 16
	v_readlane_b32 s57, v254, 17
	v_readlane_b32 s58, v254, 18
	v_readlane_b32 s59, v254, 19
	v_readlane_b32 s60, v254, 20
	v_readlane_b32 s61, v254, 21
	v_readlane_b32 s62, v254, 22
	v_readlane_b32 s63, v254, 23
	v_readlane_b32 s64, v254, 24
	v_readlane_b32 s65, v254, 25
	v_readlane_b32 s66, v254, 26
	v_readlane_b32 s67, v254, 27
	s_cbranch_scc0 .LBB0_64
	s_add_i32 s14, s86, 0xffffebf0
	s_lshl_b32 s7, s14, 5
	s_lshr_b32 s6, s14, 10
	s_and_b32 s15, s7, 0xfe0
	s_mov_b32 s7, 0
	s_lshl_b64 s[10:11], s[6:7], 25
	s_add_u32 s0, s0, s10
	s_addc_u32 s1, s1, s11
	s_lshl_b32 s10, s15, 13
	s_add_u32 s0, s0, s10
	s_addc_u32 s1, s1, 0
	s_lshl_b64 s[6:7], s[6:7], 26
	s_add_u32 s4, s4, s6
	s_addc_u32 s5, s5, s7
	s_lshl_b32 s6, s15, 2
	s_add_u32 s6, s4, s6
	s_addc_u32 s7, s5, 0
	s_lshl_b32 s4, s14, 2
	s_and_b32 s4, s4, 0xe00
	s_mov_b64 s[10:11], 0x1000
	s_cbranch_execz .LBB0_65
	s_branch .LBB0_74

.LBB0_77:
	v_cvt_pk_bf16_f32 v95, v36, v67
	ds_write_b16 v83, v95
	v_cvt_pk_bf16_f32 v95, v37, v67
	ds_write_b16 v83, v95 offset:1040
	v_cvt_pk_bf16_f32 v95, v38, v67
	ds_write_b16 v83, v95 offset:2080
	v_cvt_pk_bf16_f32 v95, v39, v67
	ds_write_b16 v83, v95 offset:3120
	v_cvt_pk_bf16_f32 v95, v32, v67
	ds_write_b16 v84, v95
	v_cvt_pk_bf16_f32 v95, v33, v67
	ds_write_b16 v84, v95 offset:1040
	v_cvt_pk_bf16_f32 v95, v34, v67
	ds_write_b16 v84, v95 offset:2080
	v_cvt_pk_bf16_f32 v95, v35, v67
	ds_write_b16 v84, v95 offset:3120
	v_cvt_pk_bf16_f32 v95, v44, v67
	ds_write_b16 v85, v95
	v_cvt_pk_bf16_f32 v95, v45, v67
	ds_write_b16 v85, v95 offset:1040
	v_cvt_pk_bf16_f32 v95, v46, v67
	ds_write_b16 v85, v95 offset:2080
	v_cvt_pk_bf16_f32 v95, v47, v67
	ds_write_b16 v85, v95 offset:3120
	v_cvt_pk_bf16_f32 v95, v40, v67
	ds_write_b16 v86, v95
	v_cvt_pk_bf16_f32 v95, v41, v67
	ds_write_b16 v86, v95 offset:1040
	v_cvt_pk_bf16_f32 v95, v42, v67
	ds_write_b16 v86, v95 offset:2080
	v_cvt_pk_bf16_f32 v95, v43, v67
	ds_write_b16 v86, v95 offset:3120
	v_cvt_pk_bf16_f32 v95, v52, v67
	ds_write_b16 v87, v95
	v_cvt_pk_bf16_f32 v95, v53, v67
	ds_write_b16 v87, v95 offset:1040
	v_cvt_pk_bf16_f32 v95, v54, v67
	ds_write_b16 v87, v95 offset:2080
	v_cvt_pk_bf16_f32 v95, v55, v67
	ds_write_b16 v87, v95 offset:3120
	v_cvt_pk_bf16_f32 v95, v48, v67
	ds_write_b16 v88, v95
	v_cvt_pk_bf16_f32 v95, v49, v67
	ds_write_b16 v88, v95 offset:1040
	v_cvt_pk_bf16_f32 v95, v50, v67
	ds_write_b16 v88, v95 offset:2080
	v_cvt_pk_bf16_f32 v95, v51, v67
	ds_write_b16 v88, v95 offset:3120
	v_cvt_pk_bf16_f32 v95, v60, v67
	ds_write_b16 v89, v95
	v_cvt_pk_bf16_f32 v95, v61, v67
	ds_write_b16 v89, v95 offset:1040
	v_cvt_pk_bf16_f32 v95, v62, v67
	ds_write_b16 v89, v95 offset:2080
	v_cvt_pk_bf16_f32 v95, v63, v67
	ds_write_b16 v89, v95 offset:3120
	v_cvt_pk_bf16_f32 v95, v56, v67
	ds_write_b16 v90, v95
	v_cvt_pk_bf16_f32 v95, v57, v67
	ds_write_b16 v90, v95 offset:1040
	v_cvt_pk_bf16_f32 v95, v58, v67
	s_ashr_i32 s9, s8, 31
	s_add_i32 s71, s70, s84
	ds_write_b16 v90, v95 offset:2080
	v_cvt_pk_bf16_f32 v95, v59, v67
	ds_write_b16 v90, v95 offset:3120
	s_waitcnt lgkmcnt(0)
	s_barrier
	s_lshl_b64 s[10:11], s[8:9], 1
	ds_read_b128 v[96:99], v91
	s_add_u32 s10, s6, s10
	s_addc_u32 s11, s7, s11
	v_lshl_add_u64 v[100:101], s[10:11], 0, v[66:67]
	v_lshl_add_u64 v[102:103], v[100:101], 0, v[68:69]
	s_waitcnt lgkmcnt(0)
	global_store_dwordx4 v[102:103], v[96:99], off
	ds_read_b128 v[96:99], v92
	v_lshl_add_u64 v[102:103], v[100:101], 0, v[70:71]
	s_add_i32 s68, s68, s87
	s_add_i32 s69, s69, s88
	s_cmpk_gt_i32 s71, 0xa07
	s_waitcnt lgkmcnt(0)
	global_store_dwordx4 v[102:103], v[96:99], off
	ds_read_b128 v[96:99], v93
	v_lshl_add_u64 v[102:103], v[100:101], 0, v[72:73]
	v_lshl_add_u64 v[100:101], v[100:101], 0, v[74:75]
	s_cselect_b64 s[10:11], -1, 0
	s_waitcnt lgkmcnt(0)
	global_store_dwordx4 v[102:103], v[96:99], off
	ds_read_b128 v[96:99], v94
	s_waitcnt lgkmcnt(0)
	global_store_dwordx4 v[100:101], v[96:99], off
	s_waitcnt lgkmcnt(0)
	s_barrier

.LBB0_79:
	s_add_i32 s70, s71, s84
	s_cmpk_lt_i32 s70, 0xa08
	s_cselect_b64 s[10:11], -1, 0
	s_cmpk_gt_i32 s70, 0xa07
	s_cbranch_scc1 .LBB0_93
	v_readlane_b32 s52, v254, 44
	v_readlane_b32 s53, v254, 45
	v_readlane_b32 s54, v254, 46
	v_readlane_b32 s55, v254, 47
	v_readlane_b32 s56, v254, 48
	v_readlane_b32 s57, v254, 49
	v_readlane_b32 s58, v254, 50
	v_readlane_b32 s59, v254, 51
	v_readlane_b32 s60, v254, 52
	v_readlane_b32 s61, v254, 53
	v_readlane_b32 s62, v254, 54
	v_readlane_b32 s63, v254, 55
	v_readlane_b32 s64, v254, 56
	v_readlane_b32 s65, v254, 57
	v_readlane_b32 s66, v254, 58
	v_readlane_b32 s67, v254, 59
	s_mov_b64 s[12:13], s[62:63]
	v_readlane_b32 s52, v254, 60
	v_readlane_b32 s53, v254, 61
	v_readlane_b32 s54, v254, 62
	v_readlane_b32 s55, v254, 63
	v_readlane_b32 s56, v253, 0
	v_readlane_b32 s57, v253, 1
	v_readlane_b32 s58, v253, 2
	v_readlane_b32 s59, v253, 3
	v_readlane_b32 s60, v253, 4
	v_readlane_b32 s61, v253, 5
	v_readlane_b32 s62, v253, 6
	v_readlane_b32 s63, v253, 7
	v_readlane_b32 s64, v253, 8
	v_readlane_b32 s65, v253, 9
	v_readlane_b32 s66, v253, 10
	v_readlane_b32 s67, v253, 11
	s_mov_b64 s[24:25], s[58:59]
	s_mov_b64 s[14:15], s[64:65]
	s_mov_b64 s[20:21], s[66:67]
	v_readlane_b32 s52, v254, 12
	v_readlane_b32 s53, v254, 13
	s_mov_b64 s[90:91], s[52:53]
	s_cmpk_gt_i32 s70, 0x140f
	s_mov_b64 s[34:35], -1
	v_readlane_b32 s54, v254, 14
	v_readlane_b32 s55, v254, 15
	v_readlane_b32 s56, v254, 16
	v_readlane_b32 s57, v254, 17
	v_readlane_b32 s58, v254, 18
	v_readlane_b32 s59, v254, 19
	v_readlane_b32 s60, v254, 20
	v_readlane_b32 s61, v254, 21
	v_readlane_b32 s62, v254, 22
	v_readlane_b32 s63, v254, 23
	v_readlane_b32 s64, v254, 24
	v_readlane_b32 s65, v254, 25
	v_readlane_b32 s66, v254, 26
	v_readlane_b32 s67, v254, 27
	s_cbranch_scc0 .LBB0_82
	s_add_i32 s2, s70, 0xffffebf0
	s_lshr_b32 s2, s2, 10
	s_add_i32 s5, s92, s69
	s_and_b32 s5, s5, 0xfe0
	s_lshl_b64 s[6:7], s[2:3], 25
	s_add_u32 s6, s90, s6
	s_addc_u32 s7, s91, s7
	s_lshl_b32 s8, s5, 13
	s_add_u32 s6, s6, s8
	s_addc_u32 s7, s7, 0
	s_lshl_b64 s[8:9], s[2:3], 26
	s_add_u32 s2, s24, s8
	s_addc_u32 s8, s25, s9
	s_lshl_b32 s5, s5, 2
	s_add_u32 s16, s2, s5
	s_addc_u32 s17, s8, 0
	s_add_i32 s2, s89, s68
	s_and_b32 s8, s2, 0xe00
	s_mov_b64 s[34:35], 0

.Lp0t_passa:
	v_cvt_pk_bf16_f32 v95, v0, v67
	ds_write_b16 v83, v95
	v_cvt_pk_bf16_f32 v95, v1, v67
	ds_write_b16 v83, v95 offset:1040
	v_cvt_pk_bf16_f32 v95, v2, v67
	ds_write_b16 v83, v95 offset:2080
	v_cvt_pk_bf16_f32 v95, v3, v67
	ds_write_b16 v83, v95 offset:3120
	v_cvt_pk_bf16_f32 v95, v4, v67
	ds_write_b16 v84, v95
	v_cvt_pk_bf16_f32 v95, v5, v67
	ds_write_b16 v84, v95 offset:1040
	v_cvt_pk_bf16_f32 v95, v6, v67
	ds_write_b16 v84, v95 offset:2080
	v_cvt_pk_bf16_f32 v95, v7, v67
	ds_write_b16 v84, v95 offset:3120
	v_cvt_pk_bf16_f32 v95, v8, v67
	ds_write_b16 v85, v95
	v_cvt_pk_bf16_f32 v95, v9, v67
	ds_write_b16 v85, v95 offset:1040
	v_cvt_pk_bf16_f32 v95, v10, v67
	ds_write_b16 v85, v95 offset:2080
	v_cvt_pk_bf16_f32 v95, v11, v67
	ds_write_b16 v85, v95 offset:3120
	v_cvt_pk_bf16_f32 v95, v12, v67
	ds_write_b16 v86, v95
	v_cvt_pk_bf16_f32 v95, v13, v67
	ds_write_b16 v86, v95 offset:1040
	v_cvt_pk_bf16_f32 v95, v14, v67
	ds_write_b16 v86, v95 offset:2080
	v_cvt_pk_bf16_f32 v95, v15, v67
	ds_write_b16 v86, v95 offset:3120
	v_cvt_pk_bf16_f32 v95, v16, v67
	ds_write_b16 v87, v95
	v_cvt_pk_bf16_f32 v95, v17, v67
	ds_write_b16 v87, v95 offset:1040
	v_cvt_pk_bf16_f32 v95, v18, v67
	ds_write_b16 v87, v95 offset:2080
	v_cvt_pk_bf16_f32 v95, v19, v67
	ds_write_b16 v87, v95 offset:3120
	v_cvt_pk_bf16_f32 v95, v20, v67
	ds_write_b16 v88, v95
	v_cvt_pk_bf16_f32 v95, v21, v67
	ds_write_b16 v88, v95 offset:1040
	v_cvt_pk_bf16_f32 v95, v22, v67
	ds_write_b16 v88, v95 offset:2080
	v_cvt_pk_bf16_f32 v95, v23, v67
	ds_write_b16 v88, v95 offset:3120
	v_cvt_pk_bf16_f32 v95, v24, v67
	ds_write_b16 v89, v95
	v_cvt_pk_bf16_f32 v95, v25, v67
	ds_write_b16 v89, v95 offset:1040
	v_cvt_pk_bf16_f32 v95, v26, v67
	ds_write_b16 v89, v95 offset:2080
	v_cvt_pk_bf16_f32 v95, v27, v67
	ds_write_b16 v89, v95 offset:3120
	v_cvt_pk_bf16_f32 v95, v28, v67
	ds_write_b16 v90, v95
	v_cvt_pk_bf16_f32 v95, v29, v67
	ds_write_b16 v90, v95 offset:1040
	v_cvt_pk_bf16_f32 v95, v30, v67
	s_ashr_i32 s5, s4, 31
	ds_write_b16 v90, v95 offset:2080
	v_cvt_pk_bf16_f32 v95, v31, v67
	ds_write_b16 v90, v95 offset:3120
	s_waitcnt lgkmcnt(0)
	s_barrier
	s_lshl_b64 s[12:13], s[4:5], 1
	ds_read_b128 v[96:99], v91
	s_add_u32 s12, s0, s12
	s_addc_u32 s13, s1, s13
	v_lshl_add_u64 v[100:101], s[12:13], 0, v[66:67]
	v_lshl_add_u64 v[102:103], v[100:101], 0, v[68:69]
	s_waitcnt lgkmcnt(0)
	global_store_dwordx4 v[102:103], v[96:99], off
	ds_read_b128 v[96:99], v92
	v_lshl_add_u64 v[102:103], v[100:101], 0, v[70:71]
	s_andn2_b64 vcc, exec, s[10:11]
	s_mov_b64 s[10:11], -1
	s_waitcnt lgkmcnt(0)
	global_store_dwordx4 v[102:103], v[96:99], off
	ds_read_b128 v[96:99], v93
	v_lshl_add_u64 v[102:103], v[100:101], 0, v[72:73]
	v_lshl_add_u64 v[100:101], v[100:101], 0, v[74:75]
	s_waitcnt lgkmcnt(0)
	global_store_dwordx4 v[102:103], v[96:99], off
	ds_read_b128 v[96:99], v94
	s_waitcnt lgkmcnt(0)
	global_store_dwordx4 v[100:101], v[96:99], off
	s_waitcnt lgkmcnt(0)
	s_barrier
	s_cbranch_vccnz .LBB0_78
	s_add_i32 s5, s33, s71
	s_cmpk_gt_i32 s5, 0xa07
	s_cbranch_scc1 .Lp0t_77w
	v_readlane_b32 s52, v254, 44
	v_readlane_b32 s53, v254, 45
	v_readlane_b32 s54, v254, 46
	v_readlane_b32 s55, v254, 47
	v_readlane_b32 s56, v254, 48
	v_readlane_b32 s57, v254, 49
	v_readlane_b32 s58, v254, 50
	v_readlane_b32 s59, v254, 51
	v_readlane_b32 s60, v254, 52
	v_readlane_b32 s61, v254, 53
	v_readlane_b32 s62, v254, 54
	v_readlane_b32 s63, v254, 55
	v_readlane_b32 s64, v254, 56
	v_readlane_b32 s65, v254, 57
	v_readlane_b32 s66, v254, 58
	v_readlane_b32 s67, v254, 59
	s_mov_b64 s[10:11], s[62:63]
	v_readlane_b32 s52, v254, 60
	v_readlane_b32 s53, v254, 61
	v_readlane_b32 s54, v254, 62
	v_readlane_b32 s55, v254, 63
	v_readlane_b32 s56, v253, 0
	v_readlane_b32 s57, v253, 1
	v_readlane_b32 s58, v253, 2
	v_readlane_b32 s59, v253, 3
	v_readlane_b32 s60, v253, 4
	v_readlane_b32 s61, v253, 5
	v_readlane_b32 s62, v253, 6
	v_readlane_b32 s63, v253, 7
	v_readlane_b32 s64, v253, 8
	v_readlane_b32 s65, v253, 9
	v_readlane_b32 s66, v253, 10
	v_readlane_b32 s67, v253, 11
	s_mov_b64 s[20:21], s[58:59]
	s_mov_b64 s[12:13], s[64:65]
	s_mov_b64 s[16:17], s[66:67]
	v_readlane_b32 s52, v254, 12
	v_readlane_b32 s53, v254, 13
	s_mov_b64 s[34:35], s[52:53]
	s_cmpk_gt_i32 s5, 0x140f
	s_mov_b64 s[24:25], -1
	v_readlane_b32 s54, v254, 14
	v_readlane_b32 s55, v254, 15
	v_readlane_b32 s56, v254, 16
	v_readlane_b32 s57, v254, 17
	v_readlane_b32 s58, v254, 18
	v_readlane_b32 s59, v254, 19
	v_readlane_b32 s60, v254, 20
	v_readlane_b32 s61, v254, 21
	v_readlane_b32 s62, v254, 22
	v_readlane_b32 s63, v254, 23
	v_readlane_b32 s64, v254, 24
	v_readlane_b32 s65, v254, 25
	v_readlane_b32 s66, v254, 26
	v_readlane_b32 s67, v254, 27
	s_cbranch_scc0 .LBB0_97
	s_add_i32 s0, s5, 0xffffebf0
	s_lshr_b32 s2, s0, 10
	s_add_i32 s0, s88, s69
	s_and_b32 s4, s0, 0xfe0
	s_lshl_b64 s[0:1], s[2:3], 25
	s_add_u32 s0, s34, s0
	s_addc_u32 s1, s35, s1
	s_lshl_b32 s9, s4, 13
	s_add_u32 s0, s0, s9
	s_addc_u32 s1, s1, 0
	s_lshl_b64 s[14:15], s[2:3], 26
	s_add_u32 s2, s20, s14
	s_addc_u32 s9, s21, s15
	s_lshl_b32 s4, s4, 2
	s_add_u32 s14, s2, s4
	s_addc_u32 s15, s9, 0
	s_add_i32 s2, s87, s68
	s_and_b32 s4, s2, 0xe00
	s_mov_b64 s[24:25], 0

.LBB0_289:
	s_sub_u32 s0, s94, s86
	s_bfe_u32 s1, s86, 0x30003
	s_mul_i32 s1, s1, s84
	s_cmp_lg_u32 s0, s1
	s_cbranch_scc1 .Ldt0_skip
	s_mov_b32 s52, s86
	s_cmpk_lg_u32 s84, 0x100
	s_cbranch_scc1 .Ldt0_nrot
	s_xor_b32 s52, s52, 0x80
.Ldt0_nrot:
	s_addk_i32 s52, 0xa08
	s_cmpk_ge_u32 s52, 0x1c10
	s_cbranch_scc1 .Ldt0_skip
	s_waitcnt lgkmcnt(0)
	s_barrier
	v_readlane_b32 s54, v254, 54
	v_readlane_b32 s55, v254, 55
	v_readlane_b32 s56, v253, 2
	v_readlane_b32 s57, v253, 3
	v_readlane_b32 s58, v253, 8
	v_readlane_b32 s59, v253, 9
	v_readlane_b32 s60, v253, 10
	v_readlane_b32 s61, v253, 11
	v_readlane_b32 s62, v254, 12
	v_readlane_b32 s63, v254, 13
	v_and_b32_e32 v106, 7, v180
	v_lshrrev_b32_e32 v93, 3, v180
	s_add_u32 s54, s54, 0xa080000
	s_addc_u32 s55, s55, 0
	s_add_u32 s58, s58, 0x5000000
	s_addc_u32 s59, s59, 0
	s_add_u32 s60, s60, 0x40000
	s_addc_u32 s61, s61, 0
	v_lshlrev_b32_e32 v94, 4, v106
	v_bfe_u32 v107, v180, 3, 1
	v_lshlrev_b32_e32 v108, 2, v106
	v_lshl_add_u32 v108, v107, 1, v108
	v_mul_u32_u24_e32 v84, 0x410, v108
	v_lshrrev_b32_e32 v109, 3, v93
	v_xor_b32_e32 v109, v109, v106
	v_lshlrev_b32_e32 v109, 3, v109
	v_and_b32_e32 v110, 6, v93
	v_or_b32_e32 v109, v109, v110
	v_lshl_add_u32 v84, v109, 1, v84
	v_cmp_ne_u32_e64 s[74:75], 0, v107
	v_mov_b32_e32 v104, 0x1000504
	v_mov_b32_e32 v105, 0x3020706
	v_mov_b32_e32 v111, 0x5040100
	v_mov_b32_e32 v112, 0x7060302
	v_cndmask_b32_e64 v104, v104, v111, s[74:75]
	v_cndmask_b32_e64 v105, v105, v112, s[74:75]
	v_lshrrev_b32_e32 v106, 6, v180
	v_and_b32_e32 v107, 63, v180
	v_lshrrev_b32_e32 v108, 2, v106
	v_add_u32_e32 v109, 0, v108
	v_xor_b32_e32 v109, v109, v107
	v_lshlrev_b32_e32 v109, 4, v109
	v_add_u32_e32 v110, 0, v106
	v_mul_u32_u24_e32 v110, 0x410, v110
	v_add_u32_e32 v85, v109, v110
	v_add_u32_e32 v109, 2, v108
	v_xor_b32_e32 v109, v109, v107
	v_lshlrev_b32_e32 v109, 4, v109
	v_add_u32_e32 v110, 8, v106
	v_mul_u32_u24_e32 v110, 0x410, v110
	v_add_u32_e32 v86, v109, v110
	v_add_u32_e32 v109, 4, v108
	v_xor_b32_e32 v109, v109, v107
	v_lshlrev_b32_e32 v109, 4, v109
	v_add_u32_e32 v110, 16, v106
	v_mul_u32_u24_e32 v110, 0x410, v110
	v_add_u32_e32 v87, v109, v110
	v_add_u32_e32 v109, 6, v108
	v_xor_b32_e32 v109, v109, v107
	v_lshlrev_b32_e32 v109, 4, v109
	v_add_u32_e32 v110, 24, v106
	v_mul_u32_u24_e32 v110, 0x410, v110
	v_add_u32_e32 v88, v109, v110
	v_lshlrev_b32_e32 v109, 13, v106
	v_lshl_add_u32 v89, v107, 4, v109
	v_add_u32_e32 v90, 0x10000, v89
	v_add_u32_e32 v91, 0x20000, v89
	v_add_u32_e32 v92, 0x30000, v89
	s_mov_b32 s53, 0
	s_mov_b32 s73, 0
	s_cmpk_ge_u32 s52, 0x1410
	s_cbranch_scc1 .Ldt0_out0
	s_sub_i32 s0, s52, 0xa08
	s_mul_i32 s1, s0, 0xcc3
	s_lshr_b32 s1, s1, 20
	s_mul_i32 s2, s1, 0x141
	s_sub_u32 s2, s0, s2
	s_lshl_b32 s3, s2, 7
	s_mul_i32 s4, s1, 0x1410000
	s_add_u32 s3, s3, s4
	s_add_u32 s64, s54, s3
	s_addc_u32 s65, s55, 0
	s_mov_b32 s7, 0xa080
	s_lshl_b32 s4, s1, 10
	s_cmpk_lt_u32 s2, 0x80
	s_cbranch_scc1 .Ldt0_wlo0
	s_cmpk_eq_u32 s2, 0x80
	s_cbranch_scc1 .Ldt0_wlr0
	s_add_i32 s2, s2, -1
.Ldt0_wlo0:
	s_lshl_b32 s5, s2, 18
	s_add_u32 s5, s5, s4
	s_add_u32 s66, s58, s5
	s_addc_u32 s67, s59, 0
	s_branch .Ldt0_ud0
.Ldt0_wlr0:
	s_add_u32 s66, s60, s4
	s_addc_u32 s67, s61, 0
	s_branch .Ldt0_ud0
.Ldt0_out0:
	s_sub_i32 s0, s52, 0x1410
	s_lshr_b32 s1, s0, 10
	s_bfe_u32 s2, s0, 0x30007
	s_and_b32 s3, s0, 0x7f
	s_lshl_b32 s4, s1, 26
	s_lshl_b32 s5, s3, 7
	s_add_u32 s4, s4, s5
	s_lshl_b32 s5, s2, 23
	s_add_u32 s4, s4, s5
	s_add_u32 s64, s56, s4
	s_addc_u32 s65, s57, 0
	s_lshl_b32 s4, s1, 25
	s_lshl_b32 s5, s3, 18
	s_add_u32 s4, s4, s5
	s_lshl_b32 s5, s2, 10
	s_add_u32 s4, s4, s5
	s_add_u32 s66, s62, s4
	s_addc_u32 s67, s63, 0
	s_movk_i32 s7, 0x4000
.Ldt0_ud0:
	v_mul_u32_u24_e32 v96, s7, v93
	s_lshl_b32 s6, s7, 6
	v_add_u32_e32 v96, v96, v94
	v_add_u32_e32 v97, s6, v96
	v_add_u32_e32 v98, s6, v97
	v_add_u32_e32 v99, s6, v98
	v_add_u32_e32 v100, s6, v99
	v_add_u32_e32 v101, s6, v100
	v_add_u32_e32 v102, s6, v101
	v_add_u32_e32 v103, s6, v102
	global_load_dwordx4 v[4:7], v96, s[64:65]
	global_load_dwordx4 v[8:11], v97, s[64:65]
	global_load_dwordx4 v[12:15], v98, s[64:65]
	global_load_dwordx4 v[16:19], v99, s[64:65]
	global_load_dwordx4 v[20:23], v100, s[64:65]
	global_load_dwordx4 v[24:27], v101, s[64:65]
	global_load_dwordx4 v[28:31], v102, s[64:65]
	global_load_dwordx4 v[32:35], v103, s[64:65]
	s_mov_b32 s72, 1
	s_add_u32 s52, s52, s84
	s_cmpk_ge_u32 s52, 0x1c10
	s_cbranch_scc1 .Ldt0_procA
	s_cmpk_ge_u32 s52, 0x1410
	s_cbranch_scc1 .Ldt0_out1
	s_sub_i32 s0, s52, 0xa08
	s_mul_i32 s1, s0, 0xcc3
	s_lshr_b32 s1, s1, 20
	s_mul_i32 s2, s1, 0x141
	s_sub_u32 s2, s0, s2
	s_lshl_b32 s3, s2, 7
	s_mul_i32 s4, s1, 0x1410000
	s_add_u32 s3, s3, s4
	s_add_u32 s68, s54, s3
	s_addc_u32 s69, s55, 0
	s_mov_b32 s7, 0xa080
	s_lshl_b32 s4, s1, 10
	s_cmpk_lt_u32 s2, 0x80
	s_cbranch_scc1 .Ldt0_wlo1
	s_cmpk_eq_u32 s2, 0x80
	s_cbranch_scc1 .Ldt0_wlr1
	s_add_i32 s2, s2, -1
.Ldt0_wlo1:
	s_lshl_b32 s5, s2, 18
	s_add_u32 s5, s5, s4
	s_add_u32 s10, s58, s5
	s_addc_u32 s11, s59, 0
	s_branch .Ldt0_ud1
.Ldt0_wlr1:
	s_add_u32 s10, s60, s4
	s_addc_u32 s11, s61, 0
	s_branch .Ldt0_ud1
.Ldt0_out1:
	s_sub_i32 s0, s52, 0x1410
	s_lshr_b32 s1, s0, 10
	s_bfe_u32 s2, s0, 0x30007
	s_and_b32 s3, s0, 0x7f
	s_lshl_b32 s4, s1, 26
	s_lshl_b32 s5, s3, 7
	s_add_u32 s4, s4, s5
	s_lshl_b32 s5, s2, 23
	s_add_u32 s4, s4, s5
	s_add_u32 s68, s56, s4
	s_addc_u32 s69, s57, 0
	s_lshl_b32 s4, s1, 25
	s_lshl_b32 s5, s3, 18
	s_add_u32 s4, s4, s5
	s_lshl_b32 s5, s2, 10
	s_add_u32 s4, s4, s5
	s_add_u32 s10, s62, s4
	s_addc_u32 s11, s63, 0
	s_movk_i32 s7, 0x4000
.Ldt0_ud1:
	v_mul_u32_u24_e32 v96, s7, v93
	s_lshl_b32 s6, s7, 6
	v_add_u32_e32 v96, v96, v94
	v_add_u32_e32 v97, s6, v96
	v_add_u32_e32 v98, s6, v97
	v_add_u32_e32 v99, s6, v98
	v_add_u32_e32 v100, s6, v99
	v_add_u32_e32 v101, s6, v100
	v_add_u32_e32 v102, s6, v101
	v_add_u32_e32 v103, s6, v102
	global_load_dwordx4 v[36:39], v96, s[68:69]
	global_load_dwordx4 v[40:43], v97, s[68:69]
	global_load_dwordx4 v[44:47], v98, s[68:69]
	global_load_dwordx4 v[48:51], v99, s[68:69]
	global_load_dwordx4 v[52:55], v100, s[68:69]
	global_load_dwordx4 v[56:59], v101, s[68:69]
	global_load_dwordx4 v[60:63], v102, s[68:69]
	global_load_dwordx4 v[64:67], v103, s[68:69]
	s_mov_b32 s73, 1
	s_add_u32 s52, s52, s84
.Ldt0_procA:
	s_cmp_eq_u32 s73, 0
	s_cbranch_scc1 .Ldt0_w0A
	s_cmp_lt_u32 s53, 2
	s_cbranch_scc1 .Ldt0_wsA
	s_waitcnt vmcnt(16)
	s_branch .Ldt0_wdA
.Ldt0_wsA:
	s_cmp_eq_u32 s53, 0
	s_cbranch_scc1 .Ldt0_w8A
	s_waitcnt vmcnt(12)
	s_branch .Ldt0_wdA
.Ldt0_w8A:
	s_waitcnt vmcnt(8)
	s_branch .Ldt0_wdA

.Ldt0_wdA:
	v_cvt_pk_bf16_f32 v4, v4, v5
	v_cvt_pk_bf16_f32 v6, v6, v7
	v_cvt_pk_bf16_f32 v8, v8, v9
	v_cvt_pk_bf16_f32 v10, v10, v11
	v_cvt_pk_bf16_f32 v12, v12, v13
	v_cvt_pk_bf16_f32 v14, v14, v15
	v_cvt_pk_bf16_f32 v16, v16, v17
	v_cvt_pk_bf16_f32 v18, v18, v19
	v_cvt_pk_bf16_f32 v20, v20, v21
	v_cvt_pk_bf16_f32 v22, v22, v23
	v_cvt_pk_bf16_f32 v24, v24, v25
	v_cvt_pk_bf16_f32 v26, v26, v27
	v_cvt_pk_bf16_f32 v28, v28, v29
	v_cvt_pk_bf16_f32 v30, v30, v31
	v_cvt_pk_bf16_f32 v32, v32, v33
	v_cvt_pk_bf16_f32 v34, v34, v35
	v_cndmask_b32_e64 v5, v6, v4, s[74:75]
	v_cndmask_b32_e64 v7, v4, v6, s[74:75]
	v_cndmask_b32_e64 v9, v10, v8, s[74:75]
	v_cndmask_b32_e64 v11, v8, v10, s[74:75]
	v_cndmask_b32_e64 v13, v14, v12, s[74:75]
	v_cndmask_b32_e64 v15, v12, v14, s[74:75]
	v_cndmask_b32_e64 v17, v18, v16, s[74:75]
	v_cndmask_b32_e64 v19, v16, v18, s[74:75]
	v_cndmask_b32_e64 v21, v22, v20, s[74:75]
	v_cndmask_b32_e64 v23, v20, v22, s[74:75]
	v_cndmask_b32_e64 v25, v26, v24, s[74:75]
	v_cndmask_b32_e64 v27, v24, v26, s[74:75]
	v_cndmask_b32_e64 v29, v30, v28, s[74:75]
	v_cndmask_b32_e64 v31, v28, v30, s[74:75]
	v_cndmask_b32_e64 v33, v34, v32, s[74:75]
	v_cndmask_b32_e64 v35, v32, v34, s[74:75]
	v_mov_b32_dpp v4, v5 row_ror:8 row_mask:0xf bank_mask:0xf
	v_mov_b32_dpp v8, v9 row_ror:8 row_mask:0xf bank_mask:0xf
	v_mov_b32_dpp v12, v13 row_ror:8 row_mask:0xf bank_mask:0xf
	v_mov_b32_dpp v16, v17 row_ror:8 row_mask:0xf bank_mask:0xf
	v_mov_b32_dpp v20, v21 row_ror:8 row_mask:0xf bank_mask:0xf
	v_mov_b32_dpp v24, v25 row_ror:8 row_mask:0xf bank_mask:0xf
	v_mov_b32_dpp v28, v29 row_ror:8 row_mask:0xf bank_mask:0xf
	v_mov_b32_dpp v32, v33 row_ror:8 row_mask:0xf bank_mask:0xf
	s_nop 1
	v_perm_b32 v68, v7, v4, v104
	v_perm_b32 v69, v7, v4, v105
	v_perm_b32 v70, v11, v8, v104
	v_perm_b32 v71, v11, v8, v105
	v_perm_b32 v72, v15, v12, v104
	v_perm_b32 v73, v15, v12, v105
	v_perm_b32 v74, v19, v16, v104
	v_perm_b32 v75, v19, v16, v105
	v_perm_b32 v76, v23, v20, v104
	v_perm_b32 v77, v23, v20, v105
	v_perm_b32 v78, v27, v24, v104
	v_perm_b32 v79, v27, v24, v105
	v_perm_b32 v80, v31, v28, v104
	v_perm_b32 v81, v31, v28, v105
	v_perm_b32 v82, v35, v32, v104
	v_perm_b32 v83, v35, v32, v105
	s_mov_b64 s[70:71], s[66:67]
	s_mov_b32 s72, 0
	s_cmpk_ge_u32 s52, 0x1c10
	s_cbranch_scc1 .Ldt0_nlA
	s_cmpk_ge_u32 s52, 0x1410
	s_cbranch_scc1 .Ldt0_out2
	s_sub_i32 s0, s52, 0xa08
	s_mul_i32 s1, s0, 0xcc3
	s_lshr_b32 s1, s1, 20
	s_mul_i32 s2, s1, 0x141
	s_sub_u32 s2, s0, s2
	s_lshl_b32 s3, s2, 7
	s_mul_i32 s4, s1, 0x1410000
	s_add_u32 s3, s3, s4
	s_add_u32 s64, s54, s3
	s_addc_u32 s65, s55, 0
	s_mov_b32 s7, 0xa080
	s_lshl_b32 s4, s1, 10
	s_cmpk_lt_u32 s2, 0x80
	s_cbranch_scc1 .Ldt0_wlo2
	s_cmpk_eq_u32 s2, 0x80
	s_cbranch_scc1 .Ldt0_wlr2
	s_add_i32 s2, s2, -1

.Ldt0_ud2:
	v_mul_u32_u24_e32 v96, s7, v93
	s_lshl_b32 s6, s7, 6
	v_add_u32_e32 v96, v96, v94
	v_add_u32_e32 v97, s6, v96
	v_add_u32_e32 v98, s6, v97
	v_add_u32_e32 v99, s6, v98
	v_add_u32_e32 v100, s6, v99
	v_add_u32_e32 v101, s6, v100
	v_add_u32_e32 v102, s6, v101
	v_add_u32_e32 v103, s6, v102
	global_load_dwordx4 v[4:7], v96, s[64:65]
	global_load_dwordx4 v[8:11], v97, s[64:65]
	global_load_dwordx4 v[12:15], v98, s[64:65]
	global_load_dwordx4 v[16:19], v99, s[64:65]
	global_load_dwordx4 v[20:23], v100, s[64:65]
	global_load_dwordx4 v[24:27], v101, s[64:65]
	global_load_dwordx4 v[28:31], v102, s[64:65]
	global_load_dwordx4 v[32:35], v103, s[64:65]
	s_mov_b32 s72, 1
	s_add_u32 s52, s52, s84
.Ldt0_nlA:
	ds_write_b32 v84, v68 offset:0
	ds_write_b32 v84, v69 offset:1040
	ds_write_b32 v84, v70 offset:128
	ds_write_b32 v84, v71 offset:1168
	ds_write_b32 v84, v72 offset:256
	ds_write_b32 v84, v73 offset:1296
	ds_write_b32 v84, v74 offset:384
	ds_write_b32 v84, v75 offset:1424
	ds_write_b32 v84, v76 offset:512
	ds_write_b32 v84, v77 offset:1552
	ds_write_b32 v84, v78 offset:640
	ds_write_b32 v84, v79 offset:1680
	ds_write_b32 v84, v80 offset:768
	ds_write_b32 v84, v81 offset:1808
	ds_write_b32 v84, v82 offset:896
	ds_write_b32 v84, v83 offset:1936
	s_waitcnt lgkmcnt(0)
	s_barrier
	ds_read_b128 v[68:71], v85 offset:0
	ds_read_b128 v[72:75], v86 offset:0
	ds_read_b128 v[76:79], v87 offset:0
	ds_read_b128 v[80:83], v88 offset:0
	s_waitcnt lgkmcnt(3)
	global_store_dwordx4 v89, v[68:71], s[70:71]
	s_waitcnt lgkmcnt(2)
	global_store_dwordx4 v90, v[72:75], s[70:71]
	s_waitcnt lgkmcnt(1)
	global_store_dwordx4 v91, v[76:79], s[70:71]
	s_waitcnt lgkmcnt(0)
	global_store_dwordx4 v92, v[80:83], s[70:71]
	s_add_u32 s53, s53, 1
	s_cmp_eq_u32 s73, 0
	s_cbranch_scc1 .Ldt0_end
.Ldt0_procB:
	s_cmp_eq_u32 s72, 0
	s_cbranch_scc1 .Ldt0_w0B
	s_cmp_lt_u32 s53, 2
	s_cbranch_scc1 .Ldt0_wsB
	s_waitcnt vmcnt(16)
	s_branch .Ldt0_wdB

.Ldt0_wdB:
	v_cvt_pk_bf16_f32 v36, v36, v37
	v_cvt_pk_bf16_f32 v38, v38, v39
	v_cvt_pk_bf16_f32 v40, v40, v41
	v_cvt_pk_bf16_f32 v42, v42, v43
	v_cvt_pk_bf16_f32 v44, v44, v45
	v_cvt_pk_bf16_f32 v46, v46, v47
	v_cvt_pk_bf16_f32 v48, v48, v49
	v_cvt_pk_bf16_f32 v50, v50, v51
	v_cvt_pk_bf16_f32 v52, v52, v53
	v_cvt_pk_bf16_f32 v54, v54, v55
	v_cvt_pk_bf16_f32 v56, v56, v57
	v_cvt_pk_bf16_f32 v58, v58, v59
	v_cvt_pk_bf16_f32 v60, v60, v61
	v_cvt_pk_bf16_f32 v62, v62, v63
	v_cvt_pk_bf16_f32 v64, v64, v65
	v_cvt_pk_bf16_f32 v66, v66, v67
	v_cndmask_b32_e64 v37, v38, v36, s[74:75]
	v_cndmask_b32_e64 v39, v36, v38, s[74:75]
	v_cndmask_b32_e64 v41, v42, v40, s[74:75]
	v_cndmask_b32_e64 v43, v40, v42, s[74:75]
	v_cndmask_b32_e64 v45, v46, v44, s[74:75]
	v_cndmask_b32_e64 v47, v44, v46, s[74:75]
	v_cndmask_b32_e64 v49, v50, v48, s[74:75]
	v_cndmask_b32_e64 v51, v48, v50, s[74:75]
	v_cndmask_b32_e64 v53, v54, v52, s[74:75]
	v_cndmask_b32_e64 v55, v52, v54, s[74:75]
	v_cndmask_b32_e64 v57, v58, v56, s[74:75]
	v_cndmask_b32_e64 v59, v56, v58, s[74:75]
	v_cndmask_b32_e64 v61, v62, v60, s[74:75]
	v_cndmask_b32_e64 v63, v60, v62, s[74:75]
	v_cndmask_b32_e64 v65, v66, v64, s[74:75]
	v_cndmask_b32_e64 v67, v64, v66, s[74:75]
	v_mov_b32_dpp v36, v37 row_ror:8 row_mask:0xf bank_mask:0xf
	v_mov_b32_dpp v40, v41 row_ror:8 row_mask:0xf bank_mask:0xf
	v_mov_b32_dpp v44, v45 row_ror:8 row_mask:0xf bank_mask:0xf
	v_mov_b32_dpp v48, v49 row_ror:8 row_mask:0xf bank_mask:0xf
	v_mov_b32_dpp v52, v53 row_ror:8 row_mask:0xf bank_mask:0xf
	v_mov_b32_dpp v56, v57 row_ror:8 row_mask:0xf bank_mask:0xf
	v_mov_b32_dpp v60, v61 row_ror:8 row_mask:0xf bank_mask:0xf
	v_mov_b32_dpp v64, v65 row_ror:8 row_mask:0xf bank_mask:0xf
	s_nop 1
	v_perm_b32 v68, v39, v36, v104
	v_perm_b32 v69, v39, v36, v105
	v_perm_b32 v70, v43, v40, v104
	v_perm_b32 v71, v43, v40, v105
	v_perm_b32 v72, v47, v44, v104
	v_perm_b32 v73, v47, v44, v105
	v_perm_b32 v74, v51, v48, v104
	v_perm_b32 v75, v51, v48, v105
	v_perm_b32 v76, v55, v52, v104
	v_perm_b32 v77, v55, v52, v105
	v_perm_b32 v78, v59, v56, v104
	v_perm_b32 v79, v59, v56, v105
	v_perm_b32 v80, v63, v60, v104
	v_perm_b32 v81, v63, v60, v105
	v_perm_b32 v82, v67, v64, v104
	v_perm_b32 v83, v67, v64, v105
	s_mov_b64 s[70:71], s[10:11]
	s_mov_b32 s73, 0
	s_cmpk_ge_u32 s52, 0x1c10
	s_cbranch_scc1 .Ldt0_nlB
	s_cmpk_ge_u32 s52, 0x1410
	s_cbranch_scc1 .Ldt0_out3
	s_sub_i32 s0, s52, 0xa08
	s_mul_i32 s1, s0, 0xcc3
	s_lshr_b32 s1, s1, 20
	s_mul_i32 s2, s1, 0x141
	s_sub_u32 s2, s0, s2
	s_lshl_b32 s3, s2, 7
	s_mul_i32 s4, s1, 0x1410000
	s_add_u32 s3, s3, s4
	s_add_u32 s68, s54, s3
	s_addc_u32 s69, s55, 0
	s_mov_b32 s7, 0xa080
	s_lshl_b32 s4, s1, 10
	s_cmpk_lt_u32 s2, 0x80
	s_cbranch_scc1 .Ldt0_wlo3
	s_cmpk_eq_u32 s2, 0x80
	s_cbranch_scc1 .Ldt0_wlr3
	s_add_i32 s2, s2, -1

.Ldt0_nlB:
	ds_write_b32 v84, v68 offset:33280
	ds_write_b32 v84, v69 offset:34320
	ds_write_b32 v84, v70 offset:33408
	ds_write_b32 v84, v71 offset:34448
	ds_write_b32 v84, v72 offset:33536
	ds_write_b32 v84, v73 offset:34576
	ds_write_b32 v84, v74 offset:33664
	ds_write_b32 v84, v75 offset:34704
	ds_write_b32 v84, v76 offset:33792
	ds_write_b32 v84, v77 offset:34832
	ds_write_b32 v84, v78 offset:33920
	ds_write_b32 v84, v79 offset:34960
	ds_write_b32 v84, v80 offset:34048
	ds_write_b32 v84, v81 offset:35088
	ds_write_b32 v84, v82 offset:34176
	ds_write_b32 v84, v83 offset:35216
	s_waitcnt lgkmcnt(0)
	s_barrier
	ds_read_b128 v[68:71], v85 offset:33280
	ds_read_b128 v[72:75], v86 offset:33280
	ds_read_b128 v[76:79], v87 offset:33280
	ds_read_b128 v[80:83], v88 offset:33280
	s_waitcnt lgkmcnt(3)
	global_store_dwordx4 v89, v[68:71], s[70:71]
	s_waitcnt lgkmcnt(2)
	global_store_dwordx4 v90, v[72:75], s[70:71]
	s_waitcnt lgkmcnt(1)
	global_store_dwordx4 v91, v[76:79], s[70:71]
	s_waitcnt lgkmcnt(0)
	global_store_dwordx4 v92, v[80:83], s[70:71]
	s_add_u32 s53, s53, 1
	s_cmp_eq_u32 s72, 0
	s_cbranch_scc0 .Ldt0_procA
.Ldt0_end:
	s_nop 1
	s_waitcnt lgkmcnt(0)
	s_barrier
